# P2 prompt k-step loops: operand prefetch two steps ahead (second register set, parity-selected), on top of P6 tail-first order without SEAM(7)
# baseline (speedup 1.0000x reference)
.LBB0_524:
	s_cmp_gt_u32 s16, 3
	s_cselect_b64 s[40:41], -1, 0
	s_cmp_lt_u32 s16, 4
	s_cselect_b32 s15, 64, 0x80
	s_lshl_b32 s17, s56, 13
	s_and_b32 s17, s17, 0xffe000
	s_add_u32 s17, s82, s17
	s_addc_u32 s18, s88, 0
	s_and_b64 s[62:63], s[64:65], exec
	s_cselect_b32 s85, s18, s43
	s_cselect_b32 s84, s17, s42
	s_cselect_b32 s15, s15, s14
	s_and_b64 vcc, exec, s[0:1]
	s_cbranch_vccz .LBB0_530
	v_cmp_gt_u32_e64 s[42:43], s13, v61
	s_and_b64 vcc, exec, s[40:41]
	s_nop 0
	v_cndmask_b32_e64 v2, 0, v61, s[42:43]
	v_add_u32_e32 v50, s12, v2
	s_cbranch_vccz .LBB0_531
	s_lshl_b32 s0, s16, 7
	v_mov_b64_e32 v[2:3], s[58:59]
	s_add_i32 s62, s0, 0xfffffe00
	v_mad_i64_i32 v[2:3], s[0:1], v50, s89, v[2:3]
	s_mov_b32 s63, s61
	v_lshl_add_u64 v[2:3], s[62:63], 1, v[2:3]
	v_lshlrev_b32_e32 v56, 1, v60
	v_lshl_add_u64 v[34:35], v[2:3], 0, v[56:57]
	v_add_co_u32_e32 v2, vcc, 0x1000, v34
	s_mov_b64 s[0:1], 0x1000
	s_nop 0
	v_addc_co_u32_e32 v3, vcc, 0, v35, vcc
	global_load_dwordx4 v[22:25], v[2:3], off
	global_load_dwordx4 v[18:21], v[34:35], off offset:3072
	v_mov_b32_e32 v2, 0
	s_mov_b32 s17, 0
	s_mov_b32 s57, 16
	v_lshl_add_u32 v38, s16, 9, v182
	v_mov_b32_e32 v39, v63
	v_mov_b32_e32 v40, v184
	v_mov_b32_e32 v3, v2
	v_mov_b32_e32 v4, v2
	v_mov_b32_e32 v5, v2
	v_mov_b32_e32 v6, v2
	v_mov_b32_e32 v7, v2
	v_mov_b32_e32 v8, v2
	v_mov_b32_e32 v9, v2
	v_mov_b32_e32 v10, v2
	v_mov_b32_e32 v11, v2
	v_mov_b32_e32 v12, v2
	v_mov_b32_e32 v13, v2
	v_mov_b32_e32 v14, v2
	v_mov_b32_e32 v15, v2
	v_mov_b32_e32 v16, v2
	v_lshl_add_u64 v[36:37], v[34:35], 0, s[0:1]
	v_mov_b32_e32 v17, v2
	s_waitcnt vmcnt(1)
	v_lshlrev_b32_e32 v33, 16, v22
	v_and_b32_e32 v32, 0xffff0000, v22
	v_lshlrev_b32_e32 v31, 16, v23
	v_and_b32_e32 v30, 0xffff0000, v23
	v_lshlrev_b32_e32 v29, 16, v24
	v_and_b32_e32 v28, 0xffff0000, v24
	v_lshlrev_b32_e32 v27, 16, v25
	v_and_b32_e32 v26, 0xffff0000, v25
	s_mov_b32 s99, 0
	v_lshl_add_u64 v[240:241], v[34:35], 0, 32
	v_lshl_add_u64 v[242:243], v[36:37], 0, 32
	global_load_dwordx4 v[232:235], v[240:241], off offset:3072
	global_load_dwordx4 v[236:239], v[242:243], off
	s_branch .LBB0_528
.LBB0_527:
	s_or_b64 exec, exec, s[0:1]
	s_add_i32 s17, s17, 64
	s_add_i32 s57, s57, 16
	s_waitcnt vmcnt(2)
	s_xor_b32 s99, s99, 1
	s_cmp_eq_u32 s99, 0
	s_cbranch_scc0 .Lp2h_botB
	v_lshlrev_b32_e32 v33, 16, v22
	v_and_b32_e32 v32, 0xffff0000, v22
	v_lshlrev_b32_e32 v31, 16, v23
	v_and_b32_e32 v30, 0xffff0000, v23
	v_lshlrev_b32_e32 v29, 16, v24
	v_and_b32_e32 v28, 0xffff0000, v24
	v_lshlrev_b32_e32 v27, 16, v25
	v_and_b32_e32 v26, 0xffff0000, v25
	s_branch .Lp2h_botE
.Lp2h_botB:
	v_lshlrev_b32_e32 v33, 16, v236
	v_and_b32_e32 v32, 0xffff0000, v236
	v_lshlrev_b32_e32 v31, 16, v237
	v_and_b32_e32 v30, 0xffff0000, v237
	v_lshlrev_b32_e32 v29, 16, v238
	v_and_b32_e32 v28, 0xffff0000, v238
	v_lshlrev_b32_e32 v27, 16, v239
	v_and_b32_e32 v26, 0xffff0000, v239
.Lp2h_botE:
	v_add_u32_e32 v40, 0x400, v40
	s_cmpk_eq_i32 s17, 0x200
	v_add_u32_e32 v39, 2, v39
	s_cbranch_scc1 .Lp2h_exit
.LBB0_528:
	s_add_i32 s60, s57, 16
	s_min_u32 s60, s60, 0x70
	s_lshl_b64 s[0:1], s[60:61], 1
	v_lshl_add_u64 v[240:241], v[34:35], 0, s[0:1]
	v_lshl_add_u64 v[242:243], v[36:37], 0, s[0:1]
	v_add_u32_e32 v41, s17, v38
	s_waitcnt vmcnt(2)
	s_cmp_eq_u32 s99, 0
	s_cbranch_scc0 .Lp2h_topB
	v_mov_b64_e32 v[44:45], v[20:21]
	v_mov_b64_e32 v[42:43], v[18:19]
	global_load_dwordx4 v[18:21], v[240:241], off offset:3072
	global_load_dwordx4 v[22:25], v[242:243], off
	s_branch .Lp2h_mid
.Lp2h_topB:
	v_mov_b64_e32 v[44:45], v[234:235]
	v_mov_b64_e32 v[42:43], v[232:233]
	global_load_dwordx4 v[232:235], v[240:241], off offset:3072
	global_load_dwordx4 v[236:239], v[242:243], off
.Lp2h_mid:
	ds_read_b128 v[46:49], v41
	ds_read_b128 v[52:55], v41 offset:16
	v_mul_f32_e64 v41, |v33|, s80
	v_exp_f32_e32 v80, v41
	v_mul_f32_e64 v41, |v32|, s80
	v_exp_f32_e32 v81, v41
	v_mul_f32_e64 v41, |v31|, s80
	v_exp_f32_e32 v82, v41
	v_mul_f32_e64 v41, |v30|, s80
	v_exp_f32_e32 v83, v41
	v_mul_f32_e64 v41, |v29|, s80
	v_exp_f32_e32 v84, v41
	v_mul_f32_e64 v41, |v28|, s80
	v_exp_f32_e32 v85, v41
	v_mul_f32_e64 v41, |v27|, s80
	v_exp_f32_e32 v86, v41
	v_mul_f32_e64 v41, |v26|, s80
	v_exp_f32_e32 v87, v41
	v_add_f32_e32 v41, 1.0, v80
	v_rcp_f32_e32 v88, v41
	v_add_f32_e32 v41, 1.0, v81
	v_rcp_f32_e32 v89, v41
	v_add_f32_e32 v41, 1.0, v82
	v_rcp_f32_e32 v90, v41
	v_add_f32_e32 v41, 1.0, v83
	v_rcp_f32_e32 v91, v41
	v_add_f32_e32 v41, 1.0, v84
	v_rcp_f32_e32 v92, v41
	v_add_f32_e32 v41, 1.0, v85
	v_rcp_f32_e32 v93, v41
	v_add_f32_e32 v41, 1.0, v86
	v_pk_mul_f32 v[80:81], v[80:81], v[88:89]
	v_cmp_nle_f32_e32 vcc, 0, v33
	v_rcp_f32_e32 v94, v41
	v_add_f32_e32 v41, 1.0, v87
	v_cndmask_b32_e32 v33, v80, v88, vcc
	s_waitcnt lgkmcnt(1)
	v_pk_add_f32 v[96:97], v[46:47], 1.0 op_sel_hi:[1,0] neg_lo:[1,0] neg_hi:[1,0]
	v_cmp_nle_f32_e64 s[0:1], 0, v32
	v_rcp_f32_e32 v95, v41
	v_mul_f32_e32 v41, v96, v33
	v_cndmask_b32_e64 v33, v89, v81, s[0:1]
	v_cndmask_b32_e32 v32, v88, v80, vcc
	v_cndmask_b32_e64 v51, v81, v89, s[0:1]
	v_pk_fma_f32 v[32:33], v[96:97], v[32:33], v[46:47]
	v_pk_mul_f32 v[46:47], v[82:83], v[90:91]
	v_cmp_nle_f32_e32 vcc, 0, v31
	v_cmp_nle_f32_e64 s[0:1], 0, v30
	v_pk_add_f32 v[80:81], v[48:49], 1.0 op_sel_hi:[1,0] neg_lo:[1,0] neg_hi:[1,0]
	v_cndmask_b32_e32 v31, v46, v90, vcc
	v_cndmask_b32_e32 v30, v90, v46, vcc
	v_cndmask_b32_e64 v46, v47, v91, s[0:1]
	v_mul_f32_e32 v56, v80, v31
	v_cndmask_b32_e64 v31, v91, v47, s[0:1]
	v_mul_f32_e32 v71, v81, v46
	v_pk_mul_f32 v[46:47], v[84:85], v[92:93]
	v_cmp_nle_f32_e32 vcc, 0, v29
	v_cmp_nle_f32_e64 s[0:1], 0, v28
	v_pk_fma_f32 v[30:31], v[80:81], v[30:31], v[48:49]
	v_cndmask_b32_e32 v29, v46, v92, vcc
	s_waitcnt lgkmcnt(0)
	v_pk_add_f32 v[48:49], v[52:53], 1.0 op_sel_hi:[1,0] neg_lo:[1,0] neg_hi:[1,0]
	v_cndmask_b32_e32 v28, v92, v46, vcc
	v_cndmask_b32_e64 v46, v47, v93, s[0:1]
	v_mul_f32_e32 v73, v48, v29
	v_cndmask_b32_e64 v29, v93, v47, s[0:1]
	v_mul_f32_e32 v75, v49, v46
	v_pk_mul_f32 v[46:47], v[86:87], v[94:95]
	v_cmp_nle_f32_e32 vcc, 0, v27
	v_pk_fma_f32 v[28:29], v[48:49], v[28:29], v[52:53]
	v_pk_add_f32 v[48:49], v[54:55], 1.0 op_sel_hi:[1,0] neg_lo:[1,0] neg_hi:[1,0]
	v_cndmask_b32_e32 v27, v46, v94, vcc
	v_cmp_nle_f32_e64 s[0:1], 0, v26
	v_mul_f32_e32 v77, v48, v27
	v_cndmask_b32_e32 v26, v94, v46, vcc
	v_cndmask_b32_e64 v27, v95, v47, s[0:1]
	v_cndmask_b32_e64 v52, v47, v95, s[0:1]
	v_and_b32_e32 v47, 0xffff0000, v42
	v_pk_fma_f32 v[26:27], v[48:49], v[26:27], v[54:55]
	v_mul_f32_e32 v48, 0xbfb8aa3b, v47
	v_exp_f32_e32 v48, v48
	v_mul_f32_e32 v79, v49, v52
	v_lshlrev_b32_e32 v46, 16, v42
	v_and_b32_e32 v49, 0xffff0000, v43
	v_add_f32_e32 v52, 1.0, v48
	v_lshlrev_b32_e32 v48, 16, v43
	v_mul_f32_e32 v43, 0xbfb8aa3b, v48
	v_mul_f32_e32 v42, 0xbfb8aa3b, v46
	v_exp_f32_e32 v53, v43
	v_mul_f32_e32 v43, 0xbfb8aa3b, v49
	v_exp_f32_e32 v42, v42
	v_exp_f32_e32 v54, v43
	v_rcp_f32_e32 v43, v52
	v_add_f32_e32 v52, 1.0, v53
	v_add_f32_e32 v42, 1.0, v42
	v_add_f32_e32 v53, 1.0, v54
	v_rcp_f32_e32 v42, v42
	v_rcp_f32_e32 v52, v52
	v_rcp_f32_e32 v53, v53
	v_cndmask_b32_e64 v32, 1.0, v32, s[42:43]
	v_pk_mul_f32 v[42:43], v[42:43], v[46:47]
	v_cndmask_b32_e64 v33, 1.0, v33, s[42:43]
	v_pk_mul_f32 v[46:47], v[52:53], v[48:49]
	v_mov_b32_e32 v52, 1.0
	v_cndmask_b32_e64 v30, 1.0, v30, s[42:43]
	v_cndmask_b32_e64 v31, 1.0, v31, s[42:43]
	v_mov_b32_dpp v52, v32 row_shr:1 row_mask:0xf bank_mask:0xf
	v_mul_f32_e32 v32, v32, v52
	v_mov_b32_e32 v52, 1.0
	v_cndmask_b32_e64 v28, 1.0, v28, s[42:43]
	v_cndmask_b32_e64 v29, 1.0, v29, s[42:43]
	v_mov_b32_dpp v52, v33 row_shr:1 row_mask:0xf bank_mask:0xf
	v_mul_f32_e32 v33, v33, v52
	v_mov_b32_e32 v52, 1.0
	v_cndmask_b32_e64 v26, 1.0, v26, s[42:43]
	v_cndmask_b32_e64 v27, 1.0, v27, s[42:43]
	v_mov_b32_dpp v52, v30 row_shr:1 row_mask:0xf bank_mask:0xf
	v_mul_f32_e32 v30, v30, v52
	v_mov_b32_e32 v52, 1.0
	v_and_b32_e32 v55, 0xffff0000, v44
	v_mul_f32_e32 v80, 0xbfb8aa3b, v55
	v_mov_b32_dpp v52, v31 row_shr:1 row_mask:0xf bank_mask:0xf
	v_mul_f32_e32 v31, v31, v52
	v_mov_b32_e32 v52, 1.0
	v_exp_f32_e32 v80, v80
	v_lshlrev_b32_e32 v54, 16, v44
	v_mov_b32_dpp v52, v28 row_shr:1 row_mask:0xf bank_mask:0xf
	v_mul_f32_e32 v28, v28, v52
	v_mov_b32_e32 v52, 1.0
	v_add_f32_e32 v82, 1.0, v80
	v_lshlrev_b32_e32 v80, 16, v45
	v_mov_b32_dpp v52, v29 row_shr:1 row_mask:0xf bank_mask:0xf
	v_mul_f32_e32 v29, v29, v52
	v_mov_b32_e32 v52, 1.0
	v_and_b32_e32 v81, 0xffff0000, v45
	v_mul_f32_e32 v45, 0xbfb8aa3b, v80
	v_mov_b32_dpp v52, v26 row_shr:1 row_mask:0xf bank_mask:0xf
	v_mul_f32_e32 v26, v26, v52
	v_mov_b32_e32 v52, 1.0
	v_mul_f32_e32 v44, 0xbfb8aa3b, v54
	v_exp_f32_e32 v83, v45
	v_mov_b32_dpp v52, v27 row_shr:1 row_mask:0xf bank_mask:0xf
	v_mul_f32_e32 v27, v27, v52
	v_mov_b32_e32 v52, 1.0
	v_mul_f32_e32 v45, 0xbfb8aa3b, v81
	v_exp_f32_e32 v44, v44
	v_mov_b32_dpp v52, v32 row_shr:2 row_mask:0xf bank_mask:0xf
	v_mul_f32_e32 v32, v32, v52
	v_mov_b32_e32 v52, 1.0
	v_exp_f32_e32 v84, v45
	v_add_f32_e32 v44, 1.0, v44
	v_mov_b32_dpp v52, v33 row_shr:2 row_mask:0xf bank_mask:0xf
	v_mul_f32_e32 v33, v33, v52
	v_mov_b32_e32 v52, 1.0
	v_rcp_f32_e32 v45, v82
	v_add_f32_e32 v82, 1.0, v83
	v_mov_b32_dpp v52, v30 row_shr:2 row_mask:0xf bank_mask:0xf
	v_mul_f32_e32 v30, v30, v52
	v_mov_b32_e32 v52, 1.0
	v_add_f32_e32 v83, 1.0, v84
	v_rcp_f32_e32 v44, v44
	v_mov_b32_dpp v52, v31 row_shr:2 row_mask:0xf bank_mask:0xf
	v_mul_f32_e32 v31, v31, v52
	v_mov_b32_e32 v52, 1.0
	v_rcp_f32_e32 v82, v82
	v_rcp_f32_e32 v83, v83
	v_mov_b32_dpp v52, v28 row_shr:2 row_mask:0xf bank_mask:0xf
	v_mul_f32_e32 v28, v28, v52
	v_mov_b32_e32 v52, 1.0
	v_pk_mul_f32 v[44:45], v[44:45], v[54:55]
	v_pk_mul_f32 v[48:49], v[82:83], v[80:81]
	v_mov_b32_dpp v52, v29 row_shr:2 row_mask:0xf bank_mask:0xf
	v_mul_f32_e32 v29, v29, v52
	v_mov_b32_e32 v52, 1.0
	v_mul_f32_e32 v51, v97, v51
	v_cndmask_b32_e64 v41, 0, v41, s[42:43]
	v_mov_b32_dpp v52, v26 row_shr:2 row_mask:0xf bank_mask:0xf
	v_mul_f32_e32 v26, v26, v52
	v_mov_b32_e32 v52, 1.0
	v_cndmask_b32_e64 v51, 0, v51, s[42:43]
	v_cndmask_b32_e64 v56, 0, v56, s[42:43]
	v_mov_b32_dpp v52, v27 row_shr:2 row_mask:0xf bank_mask:0xf
	v_mul_f32_e32 v27, v27, v52
	v_mov_b32_e32 v52, 1.0
	v_cndmask_b32_e64 v71, 0, v71, s[42:43]
	v_cndmask_b32_e64 v73, 0, v73, s[42:43]
	v_mov_b32_dpp v52, v32 row_shr:4 row_mask:0xf bank_mask:0xf
	v_mul_f32_e32 v32, v32, v52
	v_mov_b32_e32 v52, 1.0
	v_cndmask_b32_e64 v75, 0, v75, s[42:43]
	v_cndmask_b32_e64 v77, 0, v77, s[42:43]
	v_mov_b32_dpp v52, v33 row_shr:4 row_mask:0xf bank_mask:0xf
	v_mul_f32_e32 v33, v33, v52
	v_mov_b32_e32 v52, 1.0
	v_cndmask_b32_e64 v79, 0, v79, s[42:43]
	v_cndmask_b32_e64 v49, 0, v49, s[42:43]
	v_mov_b32_dpp v52, v30 row_shr:4 row_mask:0xf bank_mask:0xf
	v_mul_f32_e32 v30, v30, v52
	v_mov_b32_e32 v52, 1.0
	v_cndmask_b32_e64 v48, 0, v48, s[42:43]
	v_cndmask_b32_e64 v47, 0, v47, s[42:43]
	v_mov_b32_dpp v52, v31 row_shr:4 row_mask:0xf bank_mask:0xf
	v_mul_f32_e32 v31, v31, v52
	v_mov_b32_e32 v52, 1.0
	v_cndmask_b32_e64 v46, 0, v46, s[42:43]
	v_cndmask_b32_e64 v45, 0, v45, s[42:43]
	v_mov_b32_dpp v52, v28 row_shr:4 row_mask:0xf bank_mask:0xf
	v_mul_f32_e32 v28, v28, v52
	v_mov_b32_e32 v52, 1.0
	v_cndmask_b32_e64 v44, 0, v44, s[42:43]
	v_cndmask_b32_e64 v43, 0, v43, s[42:43]
	v_mov_b32_dpp v52, v29 row_shr:4 row_mask:0xf bank_mask:0xf
	v_mul_f32_e32 v29, v29, v52
	v_mov_b32_e32 v52, 1.0
	v_cndmask_b32_e64 v42, 0, v42, s[42:43]
	s_nop 0
	v_mov_b32_dpp v52, v26 row_shr:4 row_mask:0xf bank_mask:0xf
	v_mul_f32_e32 v26, v26, v52
	v_mov_b32_e32 v52, 1.0
	s_nop 1
	v_mov_b32_dpp v52, v27 row_shr:4 row_mask:0xf bank_mask:0xf
	v_mul_f32_e32 v27, v27, v52
	v_mov_b32_e32 v52, 1.0
	s_nop 1
	v_mov_b32_dpp v52, v32 row_shr:8 row_mask:0xf bank_mask:0xf
	v_mul_f32_e32 v32, v32, v52
	v_mov_b32_e32 v52, 1.0
	s_nop 1
	v_mov_b32_dpp v52, v33 row_shr:8 row_mask:0xf bank_mask:0xf
	v_mul_f32_e32 v33, v33, v52
	v_mov_b32_e32 v52, 1.0
	s_nop 1
	v_mov_b32_dpp v52, v30 row_shr:8 row_mask:0xf bank_mask:0xf
	v_mul_f32_e32 v30, v30, v52
	v_mov_b32_e32 v52, 1.0
	s_nop 1
	v_mov_b32_dpp v52, v31 row_shr:8 row_mask:0xf bank_mask:0xf
	v_mul_f32_e32 v31, v31, v52
	v_mov_b32_e32 v52, 1.0
	s_nop 1
	v_mov_b32_dpp v52, v28 row_shr:8 row_mask:0xf bank_mask:0xf
	v_mul_f32_e32 v28, v28, v52
	v_mov_b32_e32 v52, 1.0
	s_nop 1
	v_mov_b32_dpp v52, v29 row_shr:8 row_mask:0xf bank_mask:0xf
	v_mul_f32_e32 v29, v29, v52
	v_mov_b32_e32 v52, 1.0
	s_nop 1
	v_mov_b32_dpp v52, v26 row_shr:8 row_mask:0xf bank_mask:0xf
	v_mul_f32_e32 v26, v26, v52
	v_mov_b32_e32 v52, 1.0
	s_nop 1
	v_mov_b32_dpp v52, v27 row_shr:8 row_mask:0xf bank_mask:0xf
	v_mul_f32_e32 v27, v27, v52
	v_mov_b32_e32 v52, 1.0
	s_nop 1
	v_mov_b32_dpp v52, v32 row_bcast:15 row_mask:0xa bank_mask:0xf
	v_mul_f32_e32 v32, v32, v52
	v_mov_b32_e32 v52, 1.0
	s_nop 1
	v_mov_b32_dpp v52, v33 row_bcast:15 row_mask:0xa bank_mask:0xf
	v_mul_f32_e32 v33, v33, v52
	v_mov_b32_e32 v52, 1.0
	v_max_f32_e32 v53, 0x554ad2e, v33
	v_rcp_f32_e32 v85, v53
	v_mov_b32_dpp v52, v30 row_bcast:15 row_mask:0xa bank_mask:0xf
	v_mul_f32_e32 v30, v30, v52
	v_mov_b32_e32 v52, 1.0
	v_max_f32_e32 v54, 0x554ad2e, v30
	v_rcp_f32_e32 v86, v54
	v_mov_b32_dpp v52, v31 row_bcast:15 row_mask:0xa bank_mask:0xf
	v_mul_f32_e32 v31, v31, v52
	v_mov_b32_e32 v52, 1.0
	v_max_f32_e32 v55, 0x554ad2e, v31
	v_rcp_f32_e32 v87, v55
	v_mov_b32_dpp v52, v28 row_bcast:15 row_mask:0xa bank_mask:0xf
	v_mul_f32_e32 v28, v28, v52
	v_mov_b32_e32 v52, 1.0
	v_max_f32_e32 v80, 0x554ad2e, v28
	v_rcp_f32_e32 v88, v80
	v_mov_b32_dpp v52, v29 row_bcast:15 row_mask:0xa bank_mask:0xf
	v_mul_f32_e32 v29, v29, v52
	v_mov_b32_e32 v52, 1.0
	v_max_f32_e32 v81, 0x554ad2e, v29
	v_rcp_f32_e32 v89, v81
	v_mov_b32_dpp v52, v26 row_bcast:15 row_mask:0xa bank_mask:0xf
	v_mul_f32_e32 v26, v26, v52
	v_mov_b32_e32 v52, 1.0
	v_max_f32_e32 v82, 0x554ad2e, v26
	v_rcp_f32_e32 v90, v82
	v_mov_b32_dpp v52, v27 row_bcast:15 row_mask:0xa bank_mask:0xf
	v_mul_f32_e32 v27, v27, v52
	v_max_f32_e32 v52, 0x554ad2e, v32
	v_max_f32_e32 v83, 0x554ad2e, v27
	v_rcp_f32_e32 v84, v52
	v_rcp_f32_e32 v91, v83
	v_readlane_b32 s0, v52, 31
	v_readlane_b32 s1, v52, 63
	v_mul_f32_e32 v41, v41, v84
	v_mov_b32_e32 v27, s0
	v_mov_b32_e32 v26, s1
	v_readlane_b32 s0, v53, 31
	v_readlane_b32 s1, v53, 63
	v_cndmask_b32_e64 v26, v26, v27, s[2:3]
	v_mov_b32_e32 v28, s0
	v_mov_b32_e32 v27, s1
	v_readlane_b32 s0, v54, 31
	v_readlane_b32 s1, v54, 63
	v_pk_mul_f32 v[42:43], v[42:43], v[52:53]
	v_mul_f32_e32 v51, v51, v85
	v_mul_f32_e32 v53, v56, v86
	v_pk_mul_f32 v[46:47], v[46:47], v[54:55]
	v_mul_f32_e32 v54, v71, v87
	v_mul_f32_e32 v71, v73, v88
	v_pk_mul_f32 v[44:45], v[44:45], v[80:81]
	v_mul_f32_e32 v75, v75, v89
	v_mul_f32_e32 v77, v77, v90
	v_pk_mul_f32 v[48:49], v[48:49], v[82:83]
	v_mul_f32_e32 v79, v79, v91
	v_cvt_pk_bf16_f32 v42, v42, v43
	v_cvt_pk_bf16_f32 v43, v46, v47
	v_cvt_pk_bf16_f32 v44, v44, v45
	v_cvt_pk_bf16_f32 v45, v48, v49
	v_cvt_pk_bf16_f32 v46, v41, v51
	v_cvt_pk_bf16_f32 v47, v53, v54
	v_cvt_pk_bf16_f32 v48, v71, v75
	v_cvt_pk_bf16_f32 v49, v77, v79
	v_cndmask_b32_e64 v27, v27, v28, s[2:3]
	v_mov_b32_e32 v28, s1
	v_mov_b32_e32 v29, s0
	v_readlane_b32 s0, v55, 31
	v_readlane_b32 s1, v55, 63
	v_cndmask_b32_e64 v28, v28, v29, s[2:3]
	v_mov_b32_e32 v30, s0
	v_mov_b32_e32 v29, s1
	v_readlane_b32 s0, v80, 31
	v_readlane_b32 s1, v80, 63
	v_mfma_f32_32x32x16_bf16 v[2:17], v[46:49], v[42:45], v[2:17]
	v_cndmask_b32_e64 v29, v29, v30, s[2:3]
	v_mov_b32_e32 v30, s1
	v_mov_b32_e32 v31, s0
	v_readlane_b32 s0, v81, 31
	v_readlane_b32 s1, v81, 63
	v_cndmask_b32_e64 v30, v30, v31, s[2:3]
	v_mov_b32_e32 v32, s0
	v_mov_b32_e32 v31, s1
	v_readlane_b32 s0, v82, 31
	v_readlane_b32 s1, v82, 63
	v_mul_f32_e32 v84, v41, v26
	v_xor_b32_e32 v41, v39, v65
	v_cndmask_b32_e64 v31, v31, v32, s[2:3]
	v_mov_b32_e32 v32, s1
	v_mov_b32_e32 v33, s0
	v_readlane_b32 s0, v83, 31
	v_readlane_b32 s1, v83, 63
	v_mul_f32_e32 v52, v51, v27
	v_lshl_add_u32 v41, v41, 4, v148
	v_cndmask_b32_e64 v32, v32, v33, s[2:3]
	v_mov_b32_e32 v33, s1
	v_mov_b32_e32 v92, s0
	v_mul_f32_e32 v56, v53, v28
	v_mul_f32_e32 v55, v54, v29
	ds_write_b128 v41, v[42:45] offset:20480
	v_cvt_pk_bf16_f32 v41, v84, v52
	v_cndmask_b32_e64 v33, v33, v92, s[2:3]
	v_mul_f32_e32 v73, v71, v30
	v_mul_f32_e32 v80, v75, v31
	ds_write_b16 v40, v41
	ds_write_b16_d16_hi v40, v41 offset:64
	v_cvt_pk_bf16_f32 v41, v56, v55
	v_mul_f32_e32 v81, v77, v32
	v_mul_f32_e32 v82, v79, v33
	ds_write_b16 v40, v41 offset:128
	ds_write_b16_d16_hi v40, v41 offset:192
	v_cvt_pk_bf16_f32 v41, v73, v80
	ds_write_b16 v40, v41 offset:256
	ds_write_b16_d16_hi v40, v41 offset:320
	v_cvt_pk_bf16_f32 v41, v81, v82
	ds_write_b16 v40, v41 offset:384
	ds_write_b16_d16_hi v40, v41 offset:448
	s_and_saveexec_b64 s[0:1], s[4:5]
	s_cbranch_execz .LBB0_527
	v_add_u32_e32 v41, s17, v183
	ds_write_b128 v41, v[26:29]
	ds_write_b128 v41, v[30:33] offset:16
	s_branch .LBB0_527
.Lp2h_exit:
	s_waitcnt vmcnt(0)
	s_branch .LBB0_532

.LBB0_561:
	v_ashrrev_i32_e32 v51, 31, v50
	v_readlane_b32 s0, v255, 19
	v_lshlrev_b64 v[2:3], 6, v[50:51]
	v_readlane_b32 s1, v255, 20
	s_lshl_b32 s62, s16, 7
	s_mov_b32 s63, s61
	v_lshl_add_u64 v[2:3], s[0:1], 0, v[2:3]
	global_load_dwordx4 v[16:19], v[2:3], off offset:48
	global_load_dwordx4 v[20:23], v[2:3], off offset:32
	global_load_dwordx4 v[24:27], v[2:3], off offset:16
	global_load_dwordx4 v[28:31], v[2:3], off
	v_mov_b64_e32 v[2:3], s[58:59]
	v_mad_i64_i32 v[2:3], s[0:1], v50, s89, v[2:3]
	v_lshl_add_u64 v[2:3], v[2:3], 0, s[62:63]
	v_lshlrev_b32_e32 v56, 1, v60
	v_lshl_add_u64 v[48:49], v[2:3], 0, v[56:57]
	global_load_dwordx4 v[32:35], v[48:49], off
	global_load_dwordx4 v[36:39], v[48:49], off offset:512
	v_mov_b32_e32 v2, 0
	s_lshl_b32 s17, s16, 6
	v_lshl_add_u32 v56, s16, 8, v59
	s_mov_b32 s57, 0
	s_mov_b32 s63, 16
	v_mov_b32_e32 v71, v63
	v_mov_b32_e32 v73, v184
	v_mov_b32_e32 v3, v2
	v_mov_b32_e32 v4, v2
	v_mov_b32_e32 v5, v2
	v_mov_b32_e32 v6, v2
	v_mov_b32_e32 v7, v2
	v_mov_b32_e32 v8, v2
	v_mov_b32_e32 v9, v2
	v_mov_b32_e32 v10, v2
	v_mov_b32_e32 v11, v2
	v_mov_b32_e32 v12, v2
	v_mov_b32_e32 v13, v2
	v_mov_b32_e32 v14, v2
	v_mov_b32_e32 v15, v2
	s_waitcnt vmcnt(5)
	v_mov_b32_e32 v110, v16
	s_waitcnt vmcnt(4)
	v_mov_b32_e32 v98, v20
	s_waitcnt vmcnt(3)
	v_mov_b32_e32 v86, v24
	s_waitcnt vmcnt(2)
	v_mov_b32_e32 v50, v28
	v_mov_b32_e32 v51, v28
	v_mov_b32_e32 v52, v28
	v_mov_b32_e32 v53, v28
	v_mov_b32_e32 v54, v29
	v_mov_b32_e32 v55, v29
	v_mov_b32_e32 v28, v29
	v_mov_b32_e32 v80, v30
	v_mov_b32_e32 v81, v30
	v_mov_b32_e32 v82, v30
	v_mov_b32_e32 v83, v30
	v_mov_b32_e32 v84, v31
	v_mov_b32_e32 v85, v31
	v_mov_b32_e32 v30, v31
	v_mov_b32_e32 v87, v24
	v_mov_b32_e32 v88, v24
	v_mov_b32_e32 v89, v24
	v_mov_b32_e32 v90, v25
	v_mov_b32_e32 v91, v25
	v_mov_b32_e32 v24, v25
	v_mov_b32_e32 v92, v26
	v_mov_b32_e32 v93, v26
	v_mov_b32_e32 v94, v26
	v_mov_b32_e32 v95, v26
	v_mov_b32_e32 v96, v27
	v_mov_b32_e32 v97, v27
	v_mov_b32_e32 v26, v27
	v_mov_b32_e32 v99, v20
	v_mov_b32_e32 v100, v20
	v_mov_b32_e32 v101, v20
	v_mov_b32_e32 v102, v21
	v_mov_b32_e32 v103, v21
	v_mov_b32_e32 v20, v21
	v_mov_b32_e32 v104, v22
	v_mov_b32_e32 v105, v22
	v_mov_b32_e32 v106, v22
	v_mov_b32_e32 v107, v22
	v_mov_b32_e32 v108, v23
	v_mov_b32_e32 v109, v23
	v_mov_b32_e32 v22, v23
	v_mov_b32_e32 v111, v16
	v_mov_b32_e32 v112, v16
	v_mov_b32_e32 v113, v16
	v_mov_b32_e32 v114, v17
	v_mov_b32_e32 v115, v17
	v_mov_b32_e32 v116, v17
	v_mov_b32_e32 v117, v17
	v_mov_b32_e32 v118, v18
	v_mov_b32_e32 v119, v18
	v_mov_b32_e32 v120, v18
	v_mov_b32_e32 v121, v18
	v_mov_b32_e32 v122, v19
	v_mov_b32_e32 v123, v19
	v_mov_b32_e32 v18, v19
	v_mov_b32_e32 v16, v2
	v_mov_b32_e32 v17, v2
	s_mov_b32 s99, 0
	v_lshl_add_u64 v[240:241], v[48:49], 0, 32
	global_load_dwordx4 v[232:235], v[240:241], off
	global_load_dwordx4 v[236:239], v[240:241], off offset:512
	s_branch .LBB0_563

.LBB0_563:
	s_add_i32 s60, s63, 16
	s_min_u32 s60, s60, 48
	v_lshl_add_u64 v[240:241], s[60:61], 1, v[48:49]
	v_add_u32_e32 v75, s57, v56
	s_waitcnt vmcnt(2)
	s_cmp_eq_u32 s99, 0
	s_cbranch_scc0 .Lp2g_topB
	v_mov_b64_e32 v[46:47], v[38:39]
	v_mov_b64_e32 v[44:45], v[36:37]
	v_mov_b64_e32 v[42:43], v[34:35]
	v_mov_b64_e32 v[40:41], v[32:33]
	global_load_dwordx4 v[32:35], v[240:241], off
	global_load_dwordx4 v[36:39], v[240:241], off offset:512
	s_branch .Lp2g_mid
.Lp2g_topB:
	v_mov_b64_e32 v[46:47], v[238:239]
	v_mov_b64_e32 v[44:45], v[236:237]
	v_mov_b64_e32 v[42:43], v[234:235]
	v_mov_b64_e32 v[40:41], v[232:233]
	global_load_dwordx4 v[232:235], v[240:241], off
	global_load_dwordx4 v[236:239], v[240:241], off offset:512
.Lp2g_mid:
	s_xor_b32 s99, s99, 1
	ds_read_b128 v[124:127], v75 offset:16384
	ds_read_b128 v[128:131], v75 offset:16400
	ds_read_b128 v[188:191], v75
	ds_read_b128 v[192:195], v75 offset:16
	ds_read_b128 v[196:199], v75 offset:1024
	ds_read_b128 v[200:203], v75 offset:1040
	ds_read_b128 v[204:207], v75 offset:2048
	ds_read_b128 v[210:213], v75 offset:2064
	ds_read_b128 v[214:217], v75 offset:3072
	ds_read_b128 v[218:221], v75 offset:3088
	s_waitcnt lgkmcnt(7)
	v_pk_fma_f32 v[126:127], v[52:53], v[190:191], v[126:127]
	v_pk_fma_f32 v[124:125], v[50:51], v[188:189], v[124:125]
	s_waitcnt lgkmcnt(6)
	v_pk_fma_f32 v[130:131], v[52:53], v[194:195], v[130:131]
	v_pk_fma_f32 v[128:129], v[50:51], v[192:193], v[128:129]
	s_waitcnt lgkmcnt(5)
	v_pk_fma_f32 v[126:127], v[28:29], v[198:199], v[126:127]
	v_pk_fma_f32 v[124:125], v[54:55], v[196:197], v[124:125]
	s_waitcnt lgkmcnt(4)
	v_pk_fma_f32 v[130:131], v[28:29], v[202:203], v[130:131]
	v_pk_fma_f32 v[128:129], v[54:55], v[200:201], v[128:129]
	s_waitcnt lgkmcnt(3)
	v_pk_fma_f32 v[126:127], v[82:83], v[206:207], v[126:127]
	v_pk_fma_f32 v[124:125], v[80:81], v[204:205], v[124:125]
	s_waitcnt lgkmcnt(2)
	v_pk_fma_f32 v[130:131], v[82:83], v[212:213], v[130:131]
	v_pk_fma_f32 v[128:129], v[80:81], v[210:211], v[128:129]
	s_waitcnt lgkmcnt(1)
	v_pk_fma_f32 v[132:133], v[30:31], v[216:217], v[126:127]
	v_pk_fma_f32 v[214:215], v[84:85], v[214:215], v[124:125]
	s_waitcnt lgkmcnt(0)
	v_pk_fma_f32 v[216:217], v[30:31], v[220:221], v[130:131]
	v_pk_fma_f32 v[218:219], v[84:85], v[218:219], v[128:129]
	ds_read_b128 v[124:127], v75 offset:4096
	ds_read_b128 v[128:131], v75 offset:4112
	ds_read_b128 v[188:191], v75 offset:5120
	ds_read_b128 v[192:195], v75 offset:5136
	ds_read_b128 v[196:199], v75 offset:6144
	ds_read_b128 v[200:203], v75 offset:6160
	ds_read_b128 v[204:207], v75 offset:7168
	ds_read_b128 v[210:213], v75 offset:7184
	s_waitcnt lgkmcnt(7)
	v_pk_fma_f32 v[126:127], v[88:89], v[126:127], v[132:133]
	v_pk_fma_f32 v[124:125], v[86:87], v[124:125], v[214:215]
	s_waitcnt lgkmcnt(6)
	v_pk_fma_f32 v[130:131], v[88:89], v[130:131], v[216:217]
	v_pk_fma_f32 v[128:129], v[86:87], v[128:129], v[218:219]
	s_waitcnt lgkmcnt(5)
	v_pk_fma_f32 v[126:127], v[24:25], v[190:191], v[126:127]
	v_pk_fma_f32 v[124:125], v[90:91], v[188:189], v[124:125]
	s_waitcnt lgkmcnt(4)
	v_pk_fma_f32 v[130:131], v[24:25], v[194:195], v[130:131]
	v_pk_fma_f32 v[128:129], v[90:91], v[192:193], v[128:129]
	s_waitcnt lgkmcnt(3)
	v_pk_fma_f32 v[126:127], v[94:95], v[198:199], v[126:127]
	v_pk_fma_f32 v[124:125], v[92:93], v[196:197], v[124:125]
	s_waitcnt lgkmcnt(2)
	v_pk_fma_f32 v[130:131], v[94:95], v[202:203], v[130:131]
	v_pk_fma_f32 v[128:129], v[92:93], v[200:201], v[128:129]
	s_waitcnt lgkmcnt(1)
	v_pk_fma_f32 v[132:133], v[26:27], v[206:207], v[126:127]
	v_pk_fma_f32 v[214:215], v[96:97], v[204:205], v[124:125]
	s_waitcnt lgkmcnt(0)
	v_pk_fma_f32 v[216:217], v[26:27], v[212:213], v[130:131]
	v_pk_fma_f32 v[218:219], v[96:97], v[210:211], v[128:129]
	ds_read_b128 v[124:127], v75 offset:8192
	ds_read_b128 v[128:131], v75 offset:8208
	ds_read_b128 v[188:191], v75 offset:9216
	ds_read_b128 v[192:195], v75 offset:9232
	ds_read_b128 v[196:199], v75 offset:10240
	ds_read_b128 v[200:203], v75 offset:10256
	ds_read_b128 v[204:207], v75 offset:11264
	ds_read_b128 v[210:213], v75 offset:11280
	s_waitcnt lgkmcnt(7)
	v_pk_fma_f32 v[126:127], v[100:101], v[126:127], v[132:133]
	v_pk_fma_f32 v[124:125], v[98:99], v[124:125], v[214:215]
	s_waitcnt lgkmcnt(6)
	v_pk_fma_f32 v[130:131], v[100:101], v[130:131], v[216:217]
	v_pk_fma_f32 v[128:129], v[98:99], v[128:129], v[218:219]
	s_waitcnt lgkmcnt(5)
	v_pk_fma_f32 v[126:127], v[20:21], v[190:191], v[126:127]
	v_pk_fma_f32 v[124:125], v[102:103], v[188:189], v[124:125]
	s_waitcnt lgkmcnt(4)
	v_pk_fma_f32 v[130:131], v[20:21], v[194:195], v[130:131]
	v_pk_fma_f32 v[128:129], v[102:103], v[192:193], v[128:129]
	s_waitcnt lgkmcnt(3)
	v_pk_fma_f32 v[126:127], v[106:107], v[198:199], v[126:127]
	v_pk_fma_f32 v[124:125], v[104:105], v[196:197], v[124:125]
	s_waitcnt lgkmcnt(2)
	v_pk_fma_f32 v[130:131], v[106:107], v[202:203], v[130:131]
	v_pk_fma_f32 v[128:129], v[104:105], v[200:201], v[128:129]
	s_waitcnt lgkmcnt(1)
	v_pk_fma_f32 v[132:133], v[22:23], v[206:207], v[126:127]
	v_pk_fma_f32 v[214:215], v[108:109], v[204:205], v[124:125]
	s_waitcnt lgkmcnt(0)
	v_pk_fma_f32 v[216:217], v[22:23], v[212:213], v[130:131]
	v_pk_fma_f32 v[218:219], v[108:109], v[210:211], v[128:129]
	ds_read_b128 v[124:127], v75 offset:12288
	ds_read_b128 v[128:131], v75 offset:12304
	ds_read_b128 v[188:191], v75 offset:13312
	ds_read_b128 v[192:195], v75 offset:13328
	ds_read_b128 v[196:199], v75 offset:14336
	ds_read_b128 v[200:203], v75 offset:14352
	ds_read_b128 v[204:207], v75 offset:15360
	ds_read_b128 v[210:213], v75 offset:15376
	s_waitcnt lgkmcnt(7)
	v_pk_fma_f32 v[124:125], v[110:111], v[124:125], v[214:215]
	s_waitcnt lgkmcnt(6)
	v_pk_fma_f32 v[130:131], v[112:113], v[130:131], v[216:217]
	s_waitcnt lgkmcnt(5)
	v_pk_fma_f32 v[124:125], v[114:115], v[188:189], v[124:125]
	v_pk_fma_f32 v[126:127], v[112:113], v[126:127], v[132:133]
	s_waitcnt lgkmcnt(4)
	v_pk_fma_f32 v[130:131], v[116:117], v[194:195], v[130:131]
	s_waitcnt lgkmcnt(3)
	v_pk_fma_f32 v[124:125], v[118:119], v[196:197], v[124:125]
	v_pk_fma_f32 v[128:129], v[110:111], v[128:129], v[218:219]
	v_pk_fma_f32 v[126:127], v[116:117], v[190:191], v[126:127]
	s_waitcnt lgkmcnt(2)
	v_pk_fma_f32 v[132:133], v[120:121], v[202:203], v[130:131]
	s_waitcnt lgkmcnt(1)
	v_pk_fma_f32 v[130:131], v[122:123], v[204:205], v[124:125]
	v_pk_fma_f32 v[128:129], v[114:115], v[192:193], v[128:129]
	v_pk_fma_f32 v[126:127], v[120:121], v[198:199], v[126:127]
	v_mul_f32_e64 v75, |v130|, s80
	v_pk_fma_f32 v[188:189], v[118:119], v[200:201], v[128:129]
	v_pk_fma_f32 v[128:129], v[18:19], v[206:207], v[126:127]
	v_exp_f32_e32 v75, v75
	s_waitcnt lgkmcnt(0)
	v_pk_fma_f32 v[124:125], v[18:19], v[212:213], v[132:133]
	v_pk_fma_f32 v[126:127], v[122:123], v[210:211], v[188:189]
	v_mul_f32_e64 v132, |v129|, s80
	v_exp_f32_e32 v187, v132
	v_mul_f32_e64 v132, |v126|, s80
	v_exp_f32_e32 v190, v132
	v_mul_f32_e64 v132, |v127|, s80
	v_exp_f32_e32 v191, v132
	v_mul_f32_e64 v132, |v124|, s80
	v_add_f32_e32 v75, 1.0, v75
	v_exp_f32_e32 v192, v132
	v_mul_f32_e64 v132, |v125|, s80
	v_cmp_gt_f32_e32 vcc, s7, v75
	v_exp_f32_e32 v193, v132
	v_mul_f32_e64 v77, |v131|, s80
	v_cndmask_b32_e64 v132, 0, 32, vcc
	v_ldexp_f32 v75, v75, v132
	v_log_f32_e32 v75, v75
	v_exp_f32_e32 v77, v77
	v_mul_f32_e64 v79, |v128|, s80
	v_exp_f32_e32 v79, v79
	v_mul_f32_e32 v132, 0x3f317217, v75
	v_fma_f32 v132, v75, s10, -v132
	v_fmac_f32_e32 v132, 0x3377d1cf, v75
	v_fmac_f32_e32 v132, 0x3f317217, v75
	v_cmp_lt_f32_e64 s[0:1], |v75|, s11
	v_min_f32_e32 v130, 0, v130
	v_min_f32_e32 v131, 0, v131
	v_cndmask_b32_e64 v75, v75, v132, s[0:1]
	v_cndmask_b32_e32 v132, 0, v186, vcc
	v_sub_f32_e32 v132, v75, v132
	v_add_f32_e32 v75, 1.0, v77
	v_cmp_gt_f32_e32 vcc, s7, v75
	v_min_f32_e32 v128, 0, v128
	v_min_f32_e32 v129, 0, v129
	v_cndmask_b32_e64 v77, 0, 32, vcc
	v_ldexp_f32 v75, v75, v77
	v_log_f32_e32 v75, v75
	v_lshlrev_b32_e32 v194, 16, v46
	v_and_b32_e32 v195, 0xffff0000, v46
	v_lshlrev_b32_e32 v196, 16, v47
	v_mul_f32_e32 v77, 0x3f317217, v75
	v_fma_f32 v77, v75, s10, -v77
	v_fmac_f32_e32 v77, 0x3377d1cf, v75
	v_fmac_f32_e32 v77, 0x3f317217, v75
	v_cmp_lt_f32_e64 s[0:1], |v75|, s11
	v_and_b32_e32 v197, 0xffff0000, v47
	v_lshlrev_b32_e32 v46, 16, v42
	v_cndmask_b32_e64 v75, v75, v77, s[0:1]
	v_cndmask_b32_e32 v77, 0, v186, vcc
	v_sub_f32_e32 v133, v75, v77
	v_add_f32_e32 v75, 1.0, v79
	v_cmp_gt_f32_e32 vcc, s7, v75
	v_lshlrev_b32_e32 v79, 16, v45
	v_and_b32_e32 v42, 0xffff0000, v42
	v_cndmask_b32_e64 v77, 0, 32, vcc
	v_ldexp_f32 v75, v75, v77
	v_log_f32_e32 v75, v75
	v_lshlrev_b32_e32 v47, 16, v43
	v_and_b32_e32 v43, 0xffff0000, v43
	v_mul_f32_e32 v203, 0x3e000000, v42
	v_mul_f32_e32 v77, 0x3f317217, v75
	v_fma_f32 v77, v75, s10, -v77
	v_fmac_f32_e32 v77, 0x3377d1cf, v75
	v_fmac_f32_e32 v77, 0x3f317217, v75
	v_cmp_lt_f32_e64 s[0:1], |v75|, s11
	v_mul_f32_e32 v205, 0x3e000000, v43
	v_min_f32_e32 v126, 0, v126
	v_cndmask_b32_e64 v75, v75, v77, s[0:1]
	v_cndmask_b32_e32 v77, 0, v186, vcc
	v_sub_f32_e32 v188, v75, v77
	v_add_f32_e32 v75, 1.0, v187
	v_cmp_gt_f32_e32 vcc, s7, v75
	v_and_b32_e32 v187, 0xffff0000, v45
	v_lshlrev_b32_e32 v45, 16, v41
	v_cndmask_b32_e64 v77, 0, 32, vcc
	v_ldexp_f32 v75, v75, v77
	v_log_f32_e32 v75, v75
	v_and_b32_e32 v41, 0xffff0000, v41
	v_mul_f32_e32 v201, 0x3e000000, v41
	v_min_f32_e32 v127, 0, v127
	v_mul_f32_e32 v77, 0x3f317217, v75
	v_fma_f32 v77, v75, s10, -v77
	v_fmac_f32_e32 v77, 0x3377d1cf, v75
	v_fmac_f32_e32 v77, 0x3f317217, v75
	v_cmp_lt_f32_e64 s[0:1], |v75|, s11
	v_mul_f32_e32 v200, 0x3e000000, v45
	v_min_f32_e32 v124, 0, v124
	v_cndmask_b32_e64 v75, v75, v77, s[0:1]
	v_cndmask_b32_e32 v77, 0, v186, vcc
	v_sub_f32_e32 v189, v75, v77
	v_add_f32_e32 v75, 1.0, v190
	v_cmp_gt_f32_e32 vcc, s7, v75
	v_pk_add_f32 v[42:43], v[128:129], v[188:189] neg_lo:[0,1] neg_hi:[0,1]
	v_min_f32_e32 v125, 0, v125
	v_cndmask_b32_e64 v77, 0, 32, vcc
	v_ldexp_f32 v75, v75, v77
	v_log_f32_e32 v75, v75
	v_pk_mul_f32 v[42:43], v[42:43], s[92:93] op_sel_hi:[1,0]
	v_mul_f32_e32 v202, 0x3e000000, v46
	v_cndmask_b32_e64 v42, 0, v42, s[42:43]
	v_mul_f32_e32 v77, 0x3f317217, v75
	v_fma_f32 v77, v75, s10, -v77
	v_fmac_f32_e32 v77, 0x3377d1cf, v75
	v_fmac_f32_e32 v77, 0x3f317217, v75
	v_cmp_lt_f32_e64 s[0:1], |v75|, s11
	v_add_f32_dpp v42, v42, v42 row_shr:1 row_mask:0xf bank_mask:0xf bound_ctrl:1
	v_cndmask_b32_e64 v43, 0, v43, s[42:43]
	v_cndmask_b32_e64 v75, v75, v77, s[0:1]
	v_cndmask_b32_e32 v77, 0, v186, vcc
	v_sub_f32_e32 v190, v75, v77
	v_add_f32_e32 v75, 1.0, v191
	v_cmp_gt_f32_e32 vcc, s7, v75
	v_add_f32_dpp v42, v42, v42 row_shr:2 row_mask:0xf bank_mask:0xf bound_ctrl:1
	v_add_f32_dpp v43, v43, v43 row_shr:1 row_mask:0xf bank_mask:0xf bound_ctrl:1
	v_cndmask_b32_e64 v77, 0, 32, vcc
	v_ldexp_f32 v75, v75, v77
	v_log_f32_e32 v75, v75
	v_add_f32_dpp v42, v42, v42 row_shr:4 row_mask:0xf bank_mask:0xf bound_ctrl:1
	v_add_f32_dpp v43, v43, v43 row_shr:2 row_mask:0xf bank_mask:0xf bound_ctrl:1
	v_mul_f32_e32 v204, 0x3e000000, v47
	v_mul_f32_e32 v77, 0x3f317217, v75
	v_fma_f32 v77, v75, s10, -v77
	v_fmac_f32_e32 v77, 0x3377d1cf, v75
	v_fmac_f32_e32 v77, 0x3f317217, v75
	v_cmp_lt_f32_e64 s[0:1], |v75|, s11
	v_add_f32_dpp v42, v42, v42 row_shr:8 row_mask:0xf bank_mask:0xf bound_ctrl:1
	v_add_f32_dpp v43, v43, v43 row_shr:4 row_mask:0xf bank_mask:0xf bound_ctrl:1
	v_cndmask_b32_e64 v75, v75, v77, s[0:1]
	v_cndmask_b32_e32 v77, 0, v186, vcc
	v_sub_f32_e32 v191, v75, v77
	v_add_f32_e32 v75, 1.0, v192
	v_cmp_gt_f32_e32 vcc, s7, v75
	v_add_f32_dpp v43, v43, v43 row_shr:8 row_mask:0xf bank_mask:0xf bound_ctrl:1
	v_cndmask_b32_e64 v128, 0, v187, s[42:43]
	v_cndmask_b32_e64 v77, 0, 32, vcc
	v_ldexp_f32 v75, v75, v77
	v_log_f32_e32 v75, v75
	v_cndmask_b32_e64 v187, 0, v196, s[42:43]
	v_cndmask_b32_e64 v189, 0, v197, s[42:43]
	v_cndmask_b32_e64 v129, 0, v202, s[42:43]
	v_mul_f32_e32 v77, 0x3f317217, v75
	v_fma_f32 v77, v75, s10, -v77
	v_fmac_f32_e32 v77, 0x3377d1cf, v75
	v_fmac_f32_e32 v77, 0x3f317217, v75
	v_cmp_lt_f32_e64 s[0:1], |v75|, s11
	v_cndmask_b32_e64 v188, 0, v205, s[42:43]
	v_cndmask_b32_e64 v79, 0, v79, s[42:43]
	v_cndmask_b32_e64 v75, v75, v77, s[0:1]
	v_cndmask_b32_e32 v77, 0, v186, vcc
	v_sub_f32_e32 v192, v75, v77
	v_add_f32_e32 v75, 1.0, v193
	v_cmp_gt_f32_e32 vcc, s7, v75
	s_nop 1
	v_cndmask_b32_e64 v77, 0, 32, vcc
	v_ldexp_f32 v75, v75, v77
	v_log_f32_e32 v75, v75
	s_nop 0
	v_mul_f32_e32 v77, 0x3f317217, v75
	v_fma_f32 v77, v75, s10, -v77
	v_fmac_f32_e32 v77, 0x3377d1cf, v75
	v_fmac_f32_e32 v77, 0x3f317217, v75
	v_cmp_lt_f32_e64 s[0:1], |v75|, s11
	s_nop 1
	v_cndmask_b32_e64 v75, v75, v77, s[0:1]
	v_cndmask_b32_e32 v77, 0, v186, vcc
	v_sub_f32_e32 v193, v75, v77
	v_lshlrev_b32_e32 v75, 16, v44
	v_and_b32_e32 v77, 0xffff0000, v44
	v_lshlrev_b32_e32 v44, 16, v40
	v_and_b32_e32 v40, 0xffff0000, v40
	v_mul_f32_e32 v199, 0x3e000000, v40
	v_pk_add_f32 v[40:41], v[130:131], v[132:133] neg_lo:[0,1] neg_hi:[0,1]
	v_mul_f32_e32 v198, 0x3e000000, v44
	v_pk_mul_f32 v[40:41], v[40:41], s[92:93] op_sel_hi:[1,0]
	v_pk_add_f32 v[44:45], v[126:127], v[190:191] neg_lo:[0,1] neg_hi:[0,1]
	v_cndmask_b32_e64 v40, 0, v40, s[42:43]
	v_cndmask_b32_e64 v41, 0, v41, s[42:43]
	v_mov_b32_e32 v190, 0
	v_add_f32_dpp v40, v40, v40 row_shr:1 row_mask:0xf bank_mask:0xf bound_ctrl:1
	v_add_f32_dpp v41, v41, v41 row_shr:1 row_mask:0xf bank_mask:0xf bound_ctrl:1
	v_pk_mul_f32 v[44:45], v[44:45], s[92:93] op_sel_hi:[1,0]
	v_add_f32_dpp v40, v40, v40 row_shr:2 row_mask:0xf bank_mask:0xf bound_ctrl:1
	v_add_f32_dpp v41, v41, v41 row_shr:2 row_mask:0xf bank_mask:0xf bound_ctrl:1
	v_cndmask_b32_e64 v44, 0, v44, s[42:43]
	v_add_f32_dpp v40, v40, v40 row_shr:4 row_mask:0xf bank_mask:0xf bound_ctrl:1
	v_add_f32_dpp v41, v41, v41 row_shr:4 row_mask:0xf bank_mask:0xf bound_ctrl:1
	v_add_f32_dpp v44, v44, v44 row_shr:1 row_mask:0xf bank_mask:0xf bound_ctrl:1
	v_add_f32_dpp v40, v40, v40 row_shr:8 row_mask:0xf bank_mask:0xf bound_ctrl:1
	v_add_f32_dpp v41, v41, v41 row_shr:8 row_mask:0xf bank_mask:0xf bound_ctrl:1
	v_pk_add_f32 v[46:47], v[124:125], v[192:193] neg_lo:[0,1] neg_hi:[0,1]
	v_mov_b32_dpp v190, v40 row_bcast:15 row_mask:0xa bank_mask:0xf bound_ctrl:1
	v_add_f32_e32 v40, v40, v190
	v_mov_b32_e32 v190, 0
	v_cndmask_b32_e64 v45, 0, v45, s[42:43]
	v_add_f32_dpp v44, v44, v44 row_shr:2 row_mask:0xf bank_mask:0xf bound_ctrl:1
	v_mov_b32_dpp v190, v41 row_bcast:15 row_mask:0xa bank_mask:0xf bound_ctrl:1
	v_add_f32_e32 v41, v41, v190
	v_mov_b32_e32 v190, 0
	v_pk_mul_f32 v[46:47], v[46:47], s[92:93] op_sel_hi:[1,0]
	v_add_f32_dpp v45, v45, v45 row_shr:1 row_mask:0xf bank_mask:0xf bound_ctrl:1
	v_mov_b32_dpp v190, v42 row_bcast:15 row_mask:0xa bank_mask:0xf bound_ctrl:1
	v_add_f32_e32 v42, v42, v190
	v_mov_b32_e32 v190, 0
	v_add_f32_dpp v44, v44, v44 row_shr:4 row_mask:0xf bank_mask:0xf bound_ctrl:1
	v_cndmask_b32_e64 v46, 0, v46, s[42:43]
	v_mov_b32_dpp v190, v43 row_bcast:15 row_mask:0xa bank_mask:0xf bound_ctrl:1
	v_add_f32_dpp v45, v45, v45 row_shr:2 row_mask:0xf bank_mask:0xf bound_ctrl:1
	v_add_f32_dpp v44, v44, v44 row_shr:8 row_mask:0xf bank_mask:0xf bound_ctrl:1
	v_add_f32_e32 v43, v43, v190
	v_mov_b32_e32 v190, 0
	v_add_f32_dpp v46, v46, v46 row_shr:1 row_mask:0xf bank_mask:0xf bound_ctrl:1
	v_add_f32_dpp v45, v45, v45 row_shr:4 row_mask:0xf bank_mask:0xf bound_ctrl:1
	v_mov_b32_dpp v190, v44 row_bcast:15 row_mask:0xa bank_mask:0xf bound_ctrl:1
	v_cndmask_b32_e64 v47, 0, v47, s[42:43]
	v_add_f32_dpp v46, v46, v46 row_shr:2 row_mask:0xf bank_mask:0xf bound_ctrl:1
	v_add_f32_dpp v45, v45, v45 row_shr:8 row_mask:0xf bank_mask:0xf bound_ctrl:1
	v_add_f32_e32 v44, v44, v190
	v_mov_b32_e32 v190, 0
	v_add_f32_dpp v47, v47, v47 row_shr:1 row_mask:0xf bank_mask:0xf bound_ctrl:1
	v_add_f32_dpp v46, v46, v46 row_shr:4 row_mask:0xf bank_mask:0xf bound_ctrl:1
	v_mov_b32_dpp v190, v45 row_bcast:15 row_mask:0xa bank_mask:0xf bound_ctrl:1
	v_add_f32_dpp v47, v47, v47 row_shr:2 row_mask:0xf bank_mask:0xf bound_ctrl:1
	v_add_f32_dpp v46, v46, v46 row_shr:8 row_mask:0xf bank_mask:0xf bound_ctrl:1
	v_add_f32_e32 v45, v45, v190
	v_mov_b32_e32 v190, 0
	v_add_f32_dpp v47, v47, v47 row_shr:4 row_mask:0xf bank_mask:0xf bound_ctrl:1
	v_max_f32_e32 v40, 0xc2a00000, v40
	v_mov_b32_dpp v190, v46 row_bcast:15 row_mask:0xa bank_mask:0xf bound_ctrl:1
	v_add_f32_dpp v47, v47, v47 row_shr:8 row_mask:0xf bank_mask:0xf bound_ctrl:1
	v_add_f32_e32 v46, v46, v190
	v_mov_b32_e32 v190, 0
	v_mul_f32_e32 v40, 0x3fb8aa3b, v40
	v_cndmask_b32_e64 v130, 0, v194, s[42:43]
	v_mov_b32_dpp v190, v47 row_bcast:15 row_mask:0xa bank_mask:0xf bound_ctrl:1
	v_add_f32_e32 v47, v47, v190
	v_exp_f32_e32 v190, v40
	v_max_f32_e32 v40, 0xc2a00000, v41
	v_mul_f32_e32 v40, 0x3fb8aa3b, v40
	v_exp_f32_e32 v191, v40
	v_max_f32_e32 v40, 0xc2a00000, v42
	v_mul_f32_e32 v40, 0x3fb8aa3b, v40
	v_exp_f32_e32 v192, v40
	v_max_f32_e32 v40, 0xc2a00000, v43
	v_mul_f32_e32 v40, 0x3fb8aa3b, v40
	v_exp_f32_e32 v193, v40
	v_max_f32_e32 v40, 0xc2a00000, v44
	v_mul_f32_e32 v40, 0x3fb8aa3b, v40
	v_exp_f32_e32 v194, v40
	v_max_f32_e32 v40, 0xc2a00000, v45
	v_mul_f32_e32 v40, 0x3fb8aa3b, v40
	v_cndmask_b32_e64 v132, 0, v195, s[42:43]
	v_exp_f32_e32 v195, v40
	v_max_f32_e32 v40, 0xc2a00000, v46
	v_mul_f32_e32 v40, 0x3fb8aa3b, v40
	v_exp_f32_e32 v196, v40
	v_max_f32_e32 v40, 0xc2a00000, v47
	v_mul_f32_e32 v40, 0x3fb8aa3b, v40
	v_exp_f32_e32 v197, v40
	v_readlane_b32 s0, v190, 31
	v_readlane_b32 s1, v190, 63
	v_cndmask_b32_e64 v124, 0, v198, s[42:43]
	v_mov_b32_e32 v41, s0
	v_mov_b32_e32 v40, s1
	v_readlane_b32 s0, v191, 31
	v_readlane_b32 s1, v191, 63
	v_cndmask_b32_e64 v40, v40, v41, s[2:3]
	v_mov_b32_e32 v42, s0
	v_mov_b32_e32 v41, s1
	v_readlane_b32 s0, v192, 31
	v_readlane_b32 s1, v192, 63
	v_cndmask_b32_e64 v125, 0, v199, s[42:43]
	v_cndmask_b32_e64 v126, 0, v200, s[42:43]
	v_cndmask_b32_e64 v127, 0, v201, s[42:43]
	v_cndmask_b32_e64 v131, 0, v203, s[42:43]
	v_cndmask_b32_e64 v133, 0, v204, s[42:43]
	v_rcp_f32_e32 v198, v190
	v_rcp_f32_e32 v199, v191
	v_rcp_f32_e32 v200, v192
	v_rcp_f32_e32 v201, v193
	v_rcp_f32_e32 v202, v194
	v_rcp_f32_e32 v203, v195
	v_rcp_f32_e32 v204, v196
	v_rcp_f32_e32 v205, v197
	v_cndmask_b32_e64 v41, v41, v42, s[2:3]
	v_mov_b32_e32 v42, s1
	v_mov_b32_e32 v43, s0
	v_readlane_b32 s0, v193, 31
	v_readlane_b32 s1, v193, 63
	v_cndmask_b32_e64 v42, v42, v43, s[2:3]
	v_mov_b32_e32 v44, s0
	v_mov_b32_e32 v43, s1
	v_readlane_b32 s0, v194, 31
	v_readlane_b32 s1, v194, 63
	v_cndmask_b32_e64 v43, v43, v44, s[2:3]
	v_mov_b32_e32 v45, s0
	v_mov_b32_e32 v44, s1
	v_readlane_b32 s0, v195, 31
	v_readlane_b32 s1, v195, 63
	v_cndmask_b32_e64 v75, 0, v75, s[42:43]
	v_cndmask_b32_e64 v77, 0, v77, s[42:43]
	v_cndmask_b32_e64 v44, v44, v45, s[2:3]
	v_mov_b32_e32 v45, s1
	v_mov_b32_e32 v46, s0
	v_cndmask_b32_e64 v45, v45, v46, s[2:3]
	v_mul_f32_e32 v124, v124, v190
	v_mul_f32_e32 v75, v75, v198
	v_mul_f32_e32 v125, v125, v191
	v_mul_f32_e32 v77, v77, v199
	v_mul_f32_e32 v126, v126, v192
	v_mul_f32_e32 v79, v79, v200
	v_mul_f32_e32 v127, v127, v193
	v_mul_f32_e32 v193, v128, v201
	v_mul_f32_e32 v128, v129, v194
	v_mul_f32_e32 v130, v130, v202
	v_mul_f32_e32 v129, v131, v195
	v_mul_f32_e32 v131, v132, v203
	v_mul_f32_e32 v187, v187, v204
	v_mul_f32_e32 v189, v189, v205
	v_mul_f32_e32 v194, v130, v44
	v_mul_f32_e32 v132, v131, v45
	v_cvt_pk_bf16_f32 v124, v124, v125
	v_cvt_pk_bf16_f32 v125, v126, v127
	v_cvt_pk_bf16_f32 v126, v128, v129
	v_cvt_pk_bf16_f32 v128, v75, v77
	v_cvt_pk_bf16_f32 v129, v79, v193
	v_cvt_pk_bf16_f32 v130, v130, v131
	v_cvt_pk_bf16_f32 v131, v187, v189
	v_mul_f32_e32 v133, v133, v196
	v_mul_f32_e32 v188, v188, v197
	v_cvt_pk_bf16_f32 v127, v133, v188
	v_readlane_b32 s0, v196, 31
	v_readlane_b32 s1, v196, 63
	v_mfma_f32_32x32x16_bf16 v[2:17], v[128:131], v[124:127], v[2:17]
	v_mul_f32_e32 v190, v40, v75
	v_xor_b32_e32 v75, v71, v168
	v_mov_b32_e32 v46, s1
	v_mov_b32_e32 v47, s0
	v_readlane_b32 s0, v197, 31
	v_readlane_b32 s1, v197, 63
	v_mul_f32_e32 v191, v77, v41
	v_lshl_add_u32 v75, v75, 4, v167
	v_cndmask_b32_e64 v46, v46, v47, s[2:3]
	v_mov_b32_e32 v47, s1
	v_mov_b32_e32 v206, s0
	v_mul_f32_e32 v192, v79, v42
	v_mul_f32_e32 v198, v193, v43
	ds_write_b128 v75, v[124:127] offset:20480
	v_cvt_pk_bf16_f32 v75, v190, v191
	v_cndmask_b32_e64 v47, v47, v206, s[2:3]
	ds_write_b16 v73, v75
	ds_write_b16_d16_hi v73, v75 offset:64
	v_cvt_pk_bf16_f32 v75, v192, v198
	v_mul_f32_e32 v195, v187, v46
	v_mul_f32_e32 v196, v189, v47
	ds_write_b16 v73, v75 offset:128
	ds_write_b16_d16_hi v73, v75 offset:192
	v_cvt_pk_bf16_f32 v75, v194, v132
	ds_write_b16 v73, v75 offset:256
	ds_write_b16_d16_hi v73, v75 offset:320
	v_cvt_pk_bf16_f32 v75, v195, v196
	ds_write_b16 v73, v75 offset:384
	ds_write_b16_d16_hi v73, v75 offset:448
	s_and_saveexec_b64 s[0:1], s[4:5]
	s_cbranch_execz .LBB0_562
	v_add_u32_e32 v75, s57, v183
	ds_write_b128 v75, v[40:43]
	ds_write_b128 v75, v[44:47] offset:16
	s_branch .LBB0_562
